# v40 + NSA compressed-branch QK: K-fragment LDS reads pipelined 4 deep into free VGPR tuples (was single-buffered with lgkmcnt(0) per MFMA)
# baseline (speedup 1.0000x reference)
.LBB0_939:
	s_cbranch_execz .LBB0_870
	s_lshl_b32 s1, s0, 2
	s_ashr_i32 s2, s0, 1
	s_and_b32 s1, s1, 4
	v_readlane_b32 s3, v240, 42
	s_add_i32 s12, s1, s3
	s_lshl_b32 s1, s2, 3
	s_add_i32 s4, s12, s1
	s_ashr_i32 s5, s4, 31
	v_lshl_or_b32 v64, s93, 6, v193
	s_ashr_i32 s3, s2, 31
	s_lshl_b64 s[4:5], s[4:5], 18
	v_readlane_b32 s1, v240, 38
	v_ashrrev_i32_e32 v65, 31, v64
	s_add_u32 s4, s1, s4
	v_readlane_b32 s1, v240, 39
	s_addc_u32 s5, s1, s5
	v_lshlrev_b64 v[0:1], 7, v[64:65]
	v_lshl_add_u64 v[0:1], s[4:5], 0, v[0:1]
	s_lshl_b64 s[2:3], s[2:3], 11
	v_lshl_add_u64 v[0:1], v[0:1], 0, v[150:151]
	v_lshl_add_u64 v[146:147], s[2:3], 0, v[64:65]
	v_readlane_b32 s2, v240, 40
	global_load_dwordx4 v[80:83], v[0:1], off
	global_load_dwordx4 v[84:87], v[0:1], off offset:32
	global_load_dwordx4 v[88:91], v[0:1], off offset:64
	global_load_dwordx4 v[92:95], v[0:1], off offset:96
	v_lshlrev_b64 v[0:1], 7, v[146:147]
	v_readlane_b32 s3, v240, 41
	v_writelane_b32 v240, s12, 18
	s_ashr_i32 s1, s0, 31
	v_lshl_add_u64 v[0:1], s[2:3], 0, v[0:1]
	s_lshl_b64 s[2:3], s[0:1], 14
	v_readlane_b32 s4, v240, 30
	v_readlane_b32 s5, v240, 31
	s_add_u32 s4, s4, s2
	s_mul_i32 s96, s12, 12
	s_addc_u32 s5, s5, s3
	v_readlane_b32 s12, v240, 32
	v_readlane_b32 s13, v240, 33
	s_add_u32 s2, s12, s2
	s_addc_u32 s3, s13, s3
	v_lshl_add_u64 v[0:1], v[0:1], 0, s[96:97]
	v_lshl_add_u64 v[4:5], s[2:3], 0, v[152:153]
	global_load_dwordx3 v[128:130], v[0:1], off
	v_add_u32_e32 v131, v159, v132
	global_load_dwordx4 v[4:7], v[4:5], off
	v_lshl_add_u64 v[0:1], s[4:5], 0, v[152:153]
	global_load_dwordx4 v[0:3], v[0:1], off
	v_lshl_add_u64 v[8:9], s[4:5], 0, v[140:141]
	global_load_dwordx4 v[8:11], v[8:9], off
	v_lshl_add_u64 v[12:13], s[2:3], 0, v[140:141]
	global_load_dwordx4 v[12:15], v[12:13], off
	s_mov_b32 s98, s0
	s_ashr_i32 s99, s0, 31
	s_lshl_b64 s[98:99], s[98:99], 18
	v_readlane_b32 s100, v240, 49
	v_readlane_b32 s101, v240, 50
	s_add_u32 s100, s100, s98
	s_addc_u32 s101, s101, s99
	v_lshl_add_u64 v[236:237], s[100:101], 0, v[152:153]
	global_load_dwordx4 v[220:223], v[236:237], off
	v_readlane_b32 s100, v240, 47
	v_readlane_b32 s101, v240, 48
	s_add_u32 s100, s100, s98
	s_addc_u32 s101, s101, s99
	v_lshl_add_u64 v[238:239], s[100:101], 0, v[152:153]
	global_load_dwordx4 v[216:219], v[238:239], off
	s_mov_b64 s[100:101], 0x2000
	v_lshl_add_u64 v[238:239], v[238:239], 0, s[100:101]
	v_lshl_add_u64 v[236:237], v[236:237], 0, s[100:101]
	global_load_dwordx4 v[224:227], v[238:239], off
	global_load_dwordx4 v[228:231], v[236:237], off
	v_cmp_lt_i32_e32 vcc, 30, v64
	s_waitcnt vmcnt(0)
	ds_write_b128 v206, v[0:3]
	ds_write_b128 v207, v[4:7] offset:18432
	s_movk_i32 s2, 0x41
	s_mov_b64 s[4:5], -1
	ds_write_b128 v208, v[8:11]
	ds_write_b128 v209, v[12:15] offset:18432
	v_subrev_u32_e32 v0, 31, v64
	s_waitcnt lgkmcnt(0)
	s_barrier
	v_lshrrev_b32_e32 v65, 4, v0
	ds_read_b128 v[100:103], v131
	ds_read_b128 v[104:107], v131 offset:32
	ds_read_b128 v[108:111], v131 offset:64
	ds_read_b128 v[112:115], v131 offset:13856
	ds_read_b128 v[116:119], v131 offset:96
	ds_read_b128 v[120:123], v131 offset:4608
	s_waitcnt lgkmcnt(5)
	v_mfma_f32_32x32x16_bf16 v[48:63], v[100:103], v[80:83], 0
	ds_read_b128 v[100:103], v131 offset:4640
	ds_read_b128 v[124:127], v131 offset:4672
	v_cndmask_b32_e32 v64, -1, v65, vcc
	v_sub_u32_e32 v64, v64, v138
	v_cmp_gt_i32_e64 s[40:41], 26, v64
	v_cmp_gt_i32_e64 s[42:43], 27, v64
	v_cmp_gt_i32_e64 s[38:39], 25, v64
	s_waitcnt lgkmcnt(6)
	v_mfma_f32_32x32x16_bf16 v[48:63], v[104:107], v[84:87], v[48:63]
	v_cmp_gt_i32_e64 s[36:37], 24, v64
	v_cmp_gt_i32_e64 s[34:35], 19, v64
	v_cmp_gt_i32_e64 s[30:31], 18, v64
	v_cmp_lt_i32_e32 vcc, -1, v64
	v_cmp_gt_i32_e64 s[28:29], 17, v64
	v_cmp_gt_i32_e64 s[26:27], 16, v64
	v_cmp_gt_i32_e64 s[14:15], 2, v64
	s_waitcnt lgkmcnt(5)
	v_mfma_f32_32x32x16_bf16 v[48:63], v[108:111], v[88:91], v[48:63]
	ds_read_b128 v[104:107], v131 offset:4704
	v_cmp_gt_i32_e64 s[16:17], 3, v64
	v_cmp_gt_i32_e64 s[24:25], 11, v64
	v_cmp_gt_i32_e64 s[18:19], 8, v64
	v_cmp_gt_i32_e64 s[20:21], 9, v64
	v_cmp_gt_i32_e64 s[22:23], 10, v64
	s_waitcnt lgkmcnt(4)
	v_mfma_f32_32x32x16_bf16 v[48:63], v[116:119], v[92:95], v[48:63]
	ds_read_b128 v[108:111], v131 offset:9216
	s_waitcnt lgkmcnt(4)
	v_mfma_f32_32x32x16_bf16 v[32:47], v[120:123], v[80:83], 0
	ds_read_b128 v[116:119], v131 offset:9248
	s_nop 7
	v_cndmask_b32_e64 v96, v62, v210, s[40:41]
	s_and_b64 s[40:41], s[42:43], s[40:41]
	v_cndmask_b32_e64 v79, v61, v210, s[38:39]
	s_and_b64 s[38:39], s[40:41], s[38:39]
	v_cndmask_b32_e64 v78, v60, v210, s[36:37]
	s_and_b64 s[36:37], s[38:39], s[36:37]
	s_waitcnt lgkmcnt(4)
	v_mfma_f32_32x32x16_bf16 v[32:47], v[100:103], v[84:87], v[32:47]
	ds_read_b128 v[100:103], v131 offset:9280
	v_cndmask_b32_e64 v77, v59, v210, s[34:35]
	s_and_b64 s[34:35], s[36:37], s[34:35]
	v_cndmask_b32_e64 v76, v58, v210, s[30:31]
	s_and_b64 s[30:31], s[34:35], s[30:31]
	v_cndmask_b32_e32 v65, v210, v48, vcc
	v_cmp_gt_i32_e32 vcc, 1, v64
	s_waitcnt lgkmcnt(4)
	v_mfma_f32_32x32x16_bf16 v[32:47], v[124:127], v[88:91], v[32:47]
	ds_read_b128 v[120:123], v131 offset:9312
	v_cndmask_b32_e64 v75, v57, v210, s[28:29]
	s_and_b64 s[28:29], s[30:31], s[28:29]
	v_cndmask_b32_e64 v74, v56, v210, s[26:27]
	s_and_b64 s[26:27], s[28:29], s[26:27]
	v_cndmask_b32_e64 v73, v55, v210, s[24:25]
	s_and_b64 s[24:25], s[26:27], s[24:25]
	s_waitcnt lgkmcnt(4)
	v_mfma_f32_32x32x16_bf16 v[32:47], v[104:107], v[92:95], v[32:47]
	ds_read_b128 v[104:107], v131 offset:13824
	v_cndmask_b32_e64 v70, v52, v210, s[18:19]
	v_cndmask_b32_e64 v71, v53, v210, s[20:21]
	v_cndmask_b32_e64 v72, v54, v210, s[22:23]
	s_and_b64 s[22:23], s[24:25], s[22:23]
	s_and_b64 s[20:21], s[22:23], s[20:21]
	s_and_b64 s[18:19], s[20:21], s[18:19]
	s_waitcnt lgkmcnt(4)
	v_mfma_f32_32x32x16_bf16 v[16:31], v[108:111], v[80:83], 0
	ds_read_b128 v[108:111], v131 offset:13888
	v_cndmask_b32_e64 v62, v62, v96, s[42:43]
	v_cndmask_b32_e64 v61, v61, v79, s[40:41]
	v_cndmask_b32_e64 v63, v63, v210, s[42:43]
	v_cmp_gt_i32_e64 s[40:41], 58, v64
	v_cmp_gt_i32_e64 s[42:43], 59, v64
	v_cndmask_b32_e64 v60, v60, v78, s[38:39]
	s_waitcnt lgkmcnt(4)
	v_mfma_f32_32x32x16_bf16 v[16:31], v[116:119], v[84:87], v[16:31]
	ds_read_b128 v[66:69], v131 offset:13920
	v_cmp_gt_i32_e64 s[38:39], 57, v64
	v_cndmask_b32_e64 v59, v59, v77, s[36:37]
	v_cmp_gt_i32_e64 s[36:37], 56, v64
	v_cndmask_b32_e64 v58, v58, v76, s[34:35]
	v_cmp_gt_i32_e64 s[34:35], 51, v64
	s_waitcnt lgkmcnt(4)
	v_mfma_f32_32x32x16_bf16 v[16:31], v[100:103], v[88:91], v[16:31]
	s_waitcnt lgkmcnt(3)
	v_mfma_f32_32x32x16_bf16 v[16:31], v[120:123], v[92:95], v[16:31]
	s_waitcnt lgkmcnt(2)
	v_mfma_f32_32x32x16_bf16 v[0:15], v[104:107], v[80:83], 0
	v_mfma_f32_32x32x16_bf16 v[0:15], v[112:115], v[84:87], v[0:15]
	s_waitcnt lgkmcnt(1)
	v_mfma_f32_32x32x16_bf16 v[0:15], v[108:111], v[88:91], v[0:15]
	s_waitcnt lgkmcnt(0)
	v_mfma_f32_32x32x16_bf16 v[0:15], v[66:69], v[92:95], v[0:15]
	v_cndmask_b32_e32 v66, v49, v210, vcc
	v_max3_f32 v67, v65, s33, v66
	v_cndmask_b32_e64 v68, v50, v210, s[14:15]
	v_cndmask_b32_e64 v69, v51, v210, s[16:17]
	v_max3_f32 v67, v67, v68, v69
	v_max3_f32 v67, v67, v70, v71
	v_max3_f32 v67, v67, v72, v73
	v_max3_f32 v67, v67, v74, v75
	s_and_b64 s[16:17], s[18:19], s[16:17]
	v_max3_f32 v67, v67, v76, v77
	s_and_b64 s[14:15], s[16:17], s[14:15]
	v_max3_f32 v67, v67, v78, v79
	s_and_b64 vcc, s[14:15], vcc
	v_cndmask_b32_e32 v65, v48, v65, vcc
	v_max3_f32 v48, v67, v96, v63
	v_cndmask_b32_e64 v96, v46, v210, s[40:41]
	s_and_b64 s[40:41], s[42:43], s[40:41]
	v_cndmask_b32_e64 v79, v45, v210, s[38:39]
	s_and_b64 s[38:39], s[40:41], s[38:39]
	v_cndmask_b32_e64 v78, v44, v210, s[36:37]
	s_and_b64 s[36:37], s[38:39], s[36:37]
	v_cndmask_b32_e64 v75, v57, v75, s[30:31]
	v_cmp_gt_i32_e64 s[30:31], 50, v64
	v_cndmask_b32_e64 v77, v43, v210, s[34:35]
	s_and_b64 s[34:35], s[36:37], s[34:35]
	v_cndmask_b32_e64 v74, v56, v74, s[28:29]
	v_cmp_gt_i32_e64 s[28:29], 49, v64
	v_cndmask_b32_e64 v76, v42, v210, s[30:31]
	s_and_b64 s[30:31], s[34:35], s[30:31]
	v_cndmask_b32_e64 v73, v55, v73, s[26:27]
	v_cmp_gt_i32_e64 s[26:27], 48, v64
	v_cndmask_b32_e64 v67, v41, v210, s[28:29]
	s_and_b64 s[28:29], s[30:31], s[28:29]
	v_cndmask_b32_e64 v72, v54, v72, s[24:25]
	v_cmp_lt_i32_e32 vcc, 31, v64
	v_cmp_gt_i32_e64 s[24:25], 43, v64
	v_cndmask_b32_e64 v57, v40, v210, s[26:27]
	s_and_b64 s[26:27], s[28:29], s[26:27]
	v_cndmask_b32_e64 v71, v53, v71, s[22:23]
	v_cndmask_b32_e64 v66, v49, v66, s[14:15]
	v_cndmask_b32_e32 v49, v210, v32, vcc
	v_cmp_gt_i32_e32 vcc, 33, v64
	v_cmp_gt_i32_e64 s[22:23], 42, v64
	v_cndmask_b32_e64 v56, v39, v210, s[24:25]
	s_and_b64 s[24:25], s[26:27], s[24:25]
	v_cndmask_b32_e64 v70, v52, v70, s[20:21]
	v_cndmask_b32_e64 v68, v50, v68, s[16:17]
	v_cndmask_b32_e32 v50, v33, v210, vcc
	v_cmp_gt_i32_e64 s[14:15], 34, v64
	v_cmp_gt_i32_e64 s[16:17], 35, v64
	v_cmp_gt_i32_e64 s[20:21], 41, v64
	v_cndmask_b32_e64 v55, v38, v210, s[22:23]
	s_and_b64 s[22:23], s[24:25], s[22:23]
	v_cndmask_b32_e64 v69, v51, v69, s[18:19]
	v_max3_f32 v48, v48, v49, v50
	v_cndmask_b32_e64 v51, v34, v210, s[14:15]
	v_cndmask_b32_e64 v52, v35, v210, s[16:17]
	v_cmp_gt_i32_e64 s[18:19], 40, v64
	v_cndmask_b32_e64 v54, v37, v210, s[20:21]
	s_and_b64 s[20:21], s[22:23], s[20:21]
	v_max3_f32 v48, v48, v51, v52
	v_cndmask_b32_e64 v53, v36, v210, s[18:19]
	s_and_b64 s[18:19], s[20:21], s[18:19]
	v_max3_f32 v48, v48, v53, v54
	s_and_b64 s[16:17], s[18:19], s[16:17]
	v_max3_f32 v48, v48, v55, v56
	s_and_b64 s[14:15], s[16:17], s[14:15]
	v_max3_f32 v48, v48, v57, v67
	s_and_b64 vcc, s[14:15], vcc
	v_max3_f32 v48, v48, v76, v77
	v_cndmask_b32_e32 v32, v32, v49, vcc
	v_cmp_lt_i32_e32 vcc, 63, v64
	v_max3_f32 v48, v48, v78, v79
	v_cndmask_b32_e64 v79, v45, v79, s[40:41]
	v_cndmask_b32_e32 v45, v210, v16, vcc
	v_cmp_gt_i32_e32 vcc, s2, v64
	s_movk_i32 s2, 0x42
	v_cndmask_b32_e64 v33, v33, v50, s[14:15]
	v_cmp_gt_i32_e64 s[14:15], s2, v64
	s_movk_i32 s2, 0x43
	v_cndmask_b32_e64 v34, v34, v51, s[16:17]
	v_cmp_gt_i32_e64 s[16:17], s2, v64
	s_movk_i32 s2, 0x48
	v_cndmask_b32_e64 v35, v35, v52, s[18:19]
	v_cmp_gt_i32_e64 s[18:19], s2, v64
	s_movk_i32 s2, 0x49
	v_cndmask_b32_e64 v36, v36, v53, s[20:21]
	v_cmp_gt_i32_e64 s[20:21], s2, v64
	s_movk_i32 s2, 0x4a
	v_cndmask_b32_e64 v37, v37, v54, s[22:23]
	v_cmp_gt_i32_e64 s[22:23], s2, v64
	s_movk_i32 s2, 0x4b
	v_cndmask_b32_e64 v38, v38, v55, s[24:25]
	v_cmp_gt_i32_e64 s[24:25], s2, v64
	s_movk_i32 s2, 0x50
	v_cndmask_b32_e64 v39, v39, v56, s[26:27]
	v_cmp_gt_i32_e64 s[26:27], s2, v64
	s_movk_i32 s2, 0x51
	v_cndmask_b32_e64 v40, v40, v57, s[28:29]
	v_cmp_gt_i32_e64 s[28:29], s2, v64
	s_movk_i32 s2, 0x52
	v_cndmask_b32_e64 v41, v41, v67, s[30:31]
	v_cmp_gt_i32_e64 s[30:31], s2, v64
	s_movk_i32 s2, 0x53
	v_cndmask_b32_e64 v42, v42, v76, s[34:35]
	v_cmp_gt_i32_e64 s[34:35], s2, v64
	s_movk_i32 s2, 0x58
	v_cndmask_b32_e64 v43, v43, v77, s[36:37]
	v_cmp_gt_i32_e64 s[36:37], s2, v64
	s_movk_i32 s2, 0x59
	v_cndmask_b32_e64 v78, v44, v78, s[38:39]
	v_cmp_gt_i32_e64 s[38:39], s2, v64
	s_movk_i32 s2, 0x5a
	v_cmp_gt_i32_e64 s[40:41], s2, v64
	s_movk_i32 s2, 0x5b
	v_cndmask_b32_e64 v97, v46, v96, s[42:43]
	v_cndmask_b32_e64 v67, v47, v210, s[42:43]
	v_cmp_gt_i32_e64 s[42:43], s2, v64
	v_max3_f32 v44, v48, v96, v67
	v_cndmask_b32_e64 v96, v30, v210, s[40:41]
	s_and_b64 s[40:41], s[42:43], s[40:41]
	v_cndmask_b32_e64 v54, v29, v210, s[38:39]
	s_and_b64 s[38:39], s[40:41], s[38:39]
	v_cndmask_b32_e64 v55, v28, v210, s[36:37]
	s_and_b64 s[36:37], s[38:39], s[36:37]
	v_cndmask_b32_e64 v77, v27, v210, s[34:35]
	s_and_b64 s[34:35], s[36:37], s[34:35]
	v_cndmask_b32_e64 v76, v26, v210, s[30:31]
	s_and_b64 s[30:31], s[34:35], s[30:31]
	v_cndmask_b32_e64 v57, v25, v210, s[28:29]
	s_and_b64 s[28:29], s[30:31], s[28:29]
	v_cndmask_b32_e64 v56, v24, v210, s[26:27]
	s_and_b64 s[26:27], s[28:29], s[26:27]
	v_cndmask_b32_e64 v53, v23, v210, s[24:25]
	s_and_b64 s[24:25], s[26:27], s[24:25]
	v_cndmask_b32_e64 v51, v22, v210, s[22:23]
	s_and_b64 s[22:23], s[24:25], s[22:23]
	v_cndmask_b32_e64 v50, v21, v210, s[20:21]
	s_and_b64 s[20:21], s[22:23], s[20:21]
	v_cndmask_b32_e64 v49, v20, v210, s[18:19]
	s_and_b64 s[18:19], s[20:21], s[18:19]
	v_cndmask_b32_e64 v48, v19, v210, s[16:17]
	s_and_b64 s[16:17], s[18:19], s[16:17]
	v_cndmask_b32_e64 v47, v18, v210, s[14:15]
	s_and_b64 s[14:15], s[16:17], s[14:15]
	v_cndmask_b32_e32 v46, v17, v210, vcc
	s_and_b64 vcc, s[14:15], vcc
	s_movk_i32 s2, 0x5f
	v_cndmask_b32_e32 v107, v16, v45, vcc
	v_cmp_lt_i32_e32 vcc, s2, v64
	s_movk_i32 s2, 0x61
	v_cndmask_b32_e64 v106, v17, v46, s[14:15]
	v_cndmask_b32_e32 v17, v210, v0, vcc
	v_cmp_gt_i32_e32 vcc, s2, v64
	s_movk_i32 s2, 0x62
	v_cmp_gt_i32_e64 s[14:15], s2, v64
	s_movk_i32 s2, 0x63
	v_cndmask_b32_e64 v105, v18, v47, s[16:17]
	v_cmp_gt_i32_e64 s[16:17], s2, v64
	s_movk_i32 s2, 0x68
	v_cndmask_b32_e64 v104, v19, v48, s[18:19]
	v_cmp_gt_i32_e64 s[18:19], s2, v64
	s_movk_i32 s2, 0x69
	v_cndmask_b32_e64 v103, v20, v49, s[20:21]
	v_cmp_gt_i32_e64 s[20:21], s2, v64
	s_movk_i32 s2, 0x6a
	v_max3_f32 v44, v44, v45, v46
	v_cndmask_b32_e64 v102, v21, v50, s[22:23]
	v_cmp_gt_i32_e64 s[22:23], s2, v64
	s_movk_i32 s2, 0x6b
	v_max3_f32 v44, v44, v47, v48
	v_cndmask_b32_e64 v101, v22, v51, s[24:25]
	v_cmp_gt_i32_e64 s[24:25], s2, v64
	s_movk_i32 s2, 0x70
	v_max3_f32 v44, v44, v49, v50
	v_cndmask_b32_e64 v100, v23, v53, s[26:27]
	v_cmp_gt_i32_e64 s[26:27], s2, v64
	s_movk_i32 s2, 0x71
	v_max3_f32 v44, v44, v51, v53
	v_cndmask_b32_e64 v99, v24, v56, s[28:29]
	v_cmp_gt_i32_e64 s[28:29], s2, v64
	s_movk_i32 s2, 0x72
	v_max3_f32 v44, v44, v56, v57
	v_cndmask_b32_e64 v98, v25, v57, s[30:31]
	v_cmp_gt_i32_e64 s[30:31], s2, v64
	s_movk_i32 s2, 0x73
	v_max3_f32 v44, v44, v76, v77
	v_cndmask_b32_e64 v76, v26, v76, s[34:35]
	v_cmp_gt_i32_e64 s[34:35], s2, v64
	s_movk_i32 s2, 0x78
	v_cndmask_b32_e64 v77, v27, v77, s[36:37]
	v_cmp_gt_i32_e64 s[36:37], s2, v64
	s_movk_i32 s2, 0x79
	v_max3_f32 v44, v44, v55, v54
	v_cndmask_b32_e64 v55, v28, v55, s[38:39]
	v_cmp_gt_i32_e64 s[38:39], s2, v64
	s_movk_i32 s2, 0x7a
	v_cndmask_b32_e64 v54, v29, v54, s[40:41]
	v_cmp_gt_i32_e64 s[40:41], s2, v64
	s_movk_i32 s2, 0x7b
	v_cndmask_b32_e64 v52, v30, v96, s[42:43]
	v_cndmask_b32_e64 v57, v31, v210, s[42:43]
	v_cmp_gt_i32_e64 s[42:43], s2, v64
	v_cndmask_b32_e64 v31, v14, v210, s[40:41]
	s_and_b64 s[40:41], s[42:43], s[40:41]
	v_cndmask_b32_e64 v30, v13, v210, s[38:39]
	s_and_b64 s[38:39], s[40:41], s[38:39]
	v_cndmask_b32_e64 v29, v12, v210, s[36:37]
	s_and_b64 s[36:37], s[38:39], s[36:37]
	v_cndmask_b32_e64 v28, v11, v210, s[34:35]
	s_and_b64 s[34:35], s[36:37], s[34:35]
	v_cndmask_b32_e64 v27, v10, v210, s[30:31]
	s_and_b64 s[30:31], s[34:35], s[30:31]
	v_cndmask_b32_e64 v26, v9, v210, s[28:29]
	s_and_b64 s[28:29], s[30:31], s[28:29]
	v_max3_f32 v16, v44, v96, v57
	v_cndmask_b32_e32 v18, v1, v210, vcc
	v_cndmask_b32_e64 v25, v8, v210, s[26:27]
	s_and_b64 s[26:27], s[28:29], s[26:27]
	v_max3_f32 v16, v16, v17, v18
	v_cndmask_b32_e64 v19, v2, v210, s[14:15]
	v_cndmask_b32_e64 v20, v3, v210, s[16:17]
	v_cndmask_b32_e64 v24, v7, v210, s[24:25]
	s_and_b64 s[24:25], s[26:27], s[24:25]
	v_max3_f32 v16, v16, v19, v20
	v_cndmask_b32_e64 v21, v4, v210, s[18:19]
	v_cndmask_b32_e64 v22, v5, v210, s[20:21]
	v_cndmask_b32_e64 v23, v6, v210, s[22:23]
	s_and_b64 s[22:23], s[24:25], s[22:23]
	v_max3_f32 v16, v16, v21, v22
	s_and_b64 s[20:21], s[22:23], s[20:21]
	v_max3_f32 v16, v16, v23, v24
	s_and_b64 s[18:19], s[20:21], s[18:19]
	v_max3_f32 v16, v16, v25, v26
	s_and_b64 s[16:17], s[18:19], s[16:17]
	v_max3_f32 v16, v16, v27, v28
	s_and_b64 s[14:15], s[16:17], s[14:15]
	v_max3_f32 v16, v16, v29, v30
	s_and_b64 vcc, s[14:15], vcc
	v_cndmask_b32_e64 v47, v15, v210, s[42:43]
	v_cndmask_b32_e32 v96, v0, v17, vcc
	v_max3_f32 v0, v16, v31, v47
	v_cndmask_b32_e64 v111, v2, v19, s[16:17]
	v_cndmask_b32_e64 v112, v1, v18, s[14:15]
	v_mov_b32_e32 v1, v0
	v_mov_b32_e32 v2, v0
	s_nop 1
	v_permlane32_swap_b32_e32 v1, v2
	v_cndmask_b32_e64 v1, v1, v2, s[6:7]
	v_max_f32_e32 v1, v1, v1
	v_max_f32_e32 v0, v0, v1
	v_cmp_neq_f32_e32 vcc, s33, v0
	v_cndmask_b32_e64 v110, v3, v20, s[18:19]
	v_cndmask_b32_e64 v109, v4, v21, s[20:21]
	v_cndmask_b32_e32 v48, 0, v0, vcc
	v_sub_f32_e32 v0, v65, v48
	v_exp_f32_e32 v0, v0
	v_sub_f32_e32 v1, v66, v48
	v_exp_f32_e32 v1, v1
	v_cndmask_b32_e64 v108, v5, v22, s[22:23]
	v_add_f32_e32 v2, 0, v0
	v_cndmask_b32_e64 v64, v6, v23, s[24:25]
	v_add_f32_e32 v3, v1, v2
	v_sub_f32_e32 v2, v68, v48
	v_exp_f32_e32 v2, v2
	v_cndmask_b32_e64 v56, v7, v24, s[26:27]
	v_cndmask_b32_e64 v53, v8, v25, s[28:29]
	v_cndmask_b32_e64 v51, v9, v26, s[30:31]
	v_add_f32_e32 v4, v2, v3
	v_sub_f32_e32 v3, v69, v48
	v_exp_f32_e32 v3, v3
	v_cndmask_b32_e64 v50, v10, v27, s[34:35]
	v_cndmask_b32_e64 v49, v11, v28, s[36:37]
	v_cndmask_b32_e64 v46, v12, v29, s[38:39]
	v_add_f32_e32 v5, v3, v4
	v_sub_f32_e32 v4, v70, v48
	v_exp_f32_e32 v4, v4
	v_cndmask_b32_e64 v45, v13, v30, s[40:41]
	v_cndmask_b32_e64 v44, v14, v31, s[42:43]
	v_sub_f32_e32 v55, v55, v48
	v_add_f32_e32 v6, v4, v5
	v_sub_f32_e32 v5, v71, v48
	v_exp_f32_e32 v5, v5
	v_sub_f32_e32 v54, v54, v48
	v_sub_f32_e32 v52, v52, v48
	v_sub_f32_e32 v53, v53, v48
	v_add_f32_e32 v7, v5, v6
	v_sub_f32_e32 v6, v72, v48
	v_exp_f32_e32 v6, v6
	v_sub_f32_e32 v51, v51, v48
	v_sub_f32_e32 v50, v50, v48
	v_sub_f32_e32 v49, v49, v48
	v_add_f32_e32 v8, v6, v7
	v_sub_f32_e32 v7, v73, v48
	v_exp_f32_e32 v7, v7
	v_sub_f32_e32 v46, v46, v48
	v_sub_f32_e32 v45, v45, v48
	v_sub_f32_e32 v44, v44, v48
	v_add_f32_e32 v9, v7, v8
	v_sub_f32_e32 v8, v74, v48
	v_exp_f32_e32 v8, v8
	s_cmp_gt_i32 s93, 7
	v_add_f32_e32 v10, v8, v9
	v_sub_f32_e32 v9, v75, v48
	v_exp_f32_e32 v9, v9
	s_nop 0
	v_add_f32_e32 v11, v9, v10
	v_sub_f32_e32 v10, v58, v48
	v_exp_f32_e32 v10, v10
	s_nop 0
	v_add_f32_e32 v12, v10, v11
	v_sub_f32_e32 v11, v59, v48
	v_exp_f32_e32 v11, v11
	s_nop 0
	v_add_f32_e32 v13, v11, v12
	v_sub_f32_e32 v12, v60, v48
	v_exp_f32_e32 v12, v12
	v_exp_f32_e32 v60, v55
	v_add_f32_e32 v14, v12, v13
	v_sub_f32_e32 v13, v61, v48
	v_exp_f32_e32 v13, v13
	v_exp_f32_e32 v61, v54
	v_add_f32_e32 v15, v13, v14
	v_sub_f32_e32 v14, v62, v48
	v_exp_f32_e32 v14, v14
	v_exp_f32_e32 v62, v52
	v_add_f32_e32 v16, v14, v15
	v_sub_f32_e32 v15, v63, v48
	v_exp_f32_e32 v15, v15
	s_nop 0
	v_add_f32_e32 v17, v15, v16
	v_sub_f32_e32 v16, v32, v48
	v_exp_f32_e32 v16, v16
	s_nop 0
	v_add_f32_e32 v18, v16, v17
	v_sub_f32_e32 v17, v33, v48
	v_exp_f32_e32 v17, v17
	s_nop 0
	v_add_f32_e32 v19, v17, v18
	v_sub_f32_e32 v18, v34, v48
	v_exp_f32_e32 v18, v18
	s_nop 0
	v_add_f32_e32 v20, v18, v19
	v_sub_f32_e32 v19, v35, v48
	v_exp_f32_e32 v19, v19
	s_nop 0
	v_add_f32_e32 v21, v19, v20
	v_sub_f32_e32 v20, v36, v48
	v_exp_f32_e32 v20, v20
	s_nop 0
	v_add_f32_e32 v22, v20, v21
	v_sub_f32_e32 v21, v37, v48
	v_exp_f32_e32 v21, v21
	s_nop 0
	v_add_f32_e32 v23, v21, v22
	v_sub_f32_e32 v22, v38, v48
	v_exp_f32_e32 v22, v22
	s_nop 0
	v_add_f32_e32 v24, v22, v23
	v_sub_f32_e32 v23, v39, v48
	v_exp_f32_e32 v23, v23
	s_nop 0
	v_add_f32_e32 v25, v23, v24
	v_sub_f32_e32 v24, v40, v48
	v_exp_f32_e32 v24, v24
	s_nop 0
	v_add_f32_e32 v26, v24, v25
	v_sub_f32_e32 v25, v41, v48
	v_exp_f32_e32 v25, v25
	s_nop 0
	v_add_f32_e32 v27, v25, v26
	v_sub_f32_e32 v26, v42, v48
	v_exp_f32_e32 v26, v26
	s_nop 0
	v_add_f32_e32 v28, v26, v27
	v_sub_f32_e32 v27, v43, v48
	v_exp_f32_e32 v27, v27
	s_nop 0
	v_add_f32_e32 v29, v27, v28
	v_sub_f32_e32 v28, v78, v48
	v_exp_f32_e32 v28, v28
	s_nop 0
	v_add_f32_e32 v30, v28, v29
	v_sub_f32_e32 v29, v79, v48
	v_exp_f32_e32 v29, v29
	s_nop 0
	v_add_f32_e32 v31, v29, v30
	v_sub_f32_e32 v30, v97, v48
	v_exp_f32_e32 v30, v30
	s_nop 0
	v_add_f32_e32 v32, v30, v31
	v_sub_f32_e32 v31, v67, v48
	v_exp_f32_e32 v31, v31
	s_nop 0
	v_add_f32_e32 v33, v31, v32
	v_sub_f32_e32 v32, v107, v48
	v_exp_f32_e32 v32, v32
	v_exp_f32_e32 v107, v49
	v_add_f32_e32 v34, v32, v33
	v_sub_f32_e32 v33, v106, v48
	v_exp_f32_e32 v33, v33
	v_exp_f32_e32 v106, v50
	v_add_f32_e32 v35, v33, v34
	v_sub_f32_e32 v34, v105, v48
	v_exp_f32_e32 v34, v34
	v_exp_f32_e32 v105, v51
	v_add_f32_e32 v36, v34, v35
	v_sub_f32_e32 v35, v104, v48
	v_exp_f32_e32 v35, v35
	v_exp_f32_e32 v104, v53
	v_add_f32_e32 v37, v35, v36
	v_sub_f32_e32 v36, v103, v48
	v_exp_f32_e32 v36, v36
	s_nop 0
	v_add_f32_e32 v38, v36, v37
	v_sub_f32_e32 v37, v102, v48
	v_exp_f32_e32 v37, v37
	s_nop 0
	v_add_f32_e32 v39, v37, v38
	v_sub_f32_e32 v38, v101, v48
	v_exp_f32_e32 v38, v38
	s_nop 0
	v_add_f32_e32 v40, v38, v39
	v_sub_f32_e32 v39, v100, v48
	v_exp_f32_e32 v39, v39
	s_nop 0
	v_add_f32_e32 v41, v39, v40
	v_sub_f32_e32 v40, v99, v48
	v_exp_f32_e32 v40, v40
	s_nop 0
	v_add_f32_e32 v42, v40, v41
	v_sub_f32_e32 v41, v98, v48
	v_exp_f32_e32 v41, v41
	s_nop 0
	v_add_f32_e32 v43, v41, v42
	v_sub_f32_e32 v42, v76, v48
	v_exp_f32_e32 v42, v42
	s_nop 0
	v_add_f32_e32 v58, v42, v43
	v_sub_f32_e32 v43, v77, v48
	v_exp_f32_e32 v43, v43
	s_nop 0
	v_add_f32_e32 v58, v43, v58
	v_add_f32_e32 v55, v60, v58
	v_add_f32_e32 v54, v61, v55
	v_add_f32_e32 v52, v62, v54
	v_sub_f32_e32 v54, v57, v48
	v_exp_f32_e32 v63, v54
	v_sub_f32_e32 v54, v96, v48
	v_exp_f32_e32 v96, v54
	v_sub_f32_e32 v54, v112, v48
	v_exp_f32_e32 v97, v54
	v_sub_f32_e32 v54, v111, v48
	v_exp_f32_e32 v98, v54
	v_sub_f32_e32 v54, v110, v48
	v_add_f32_e32 v52, v63, v52
	v_exp_f32_e32 v99, v54
	v_sub_f32_e32 v54, v109, v48
	v_add_f32_e32 v52, v96, v52
	v_exp_f32_e32 v100, v54
	v_sub_f32_e32 v54, v108, v48
	v_add_f32_e32 v52, v97, v52
	v_exp_f32_e32 v101, v54
	v_sub_f32_e32 v54, v64, v48
	v_add_f32_e32 v52, v98, v52
	v_exp_f32_e32 v102, v54
	v_sub_f32_e32 v54, v56, v48
	v_add_f32_e32 v52, v99, v52
	v_exp_f32_e32 v103, v54
	v_add_f32_e32 v52, v100, v52
	v_add_f32_e32 v52, v101, v52
	v_add_f32_e32 v52, v102, v52
	v_add_f32_e32 v52, v103, v52
	v_add_f32_e32 v52, v104, v52
	v_exp_f32_e32 v108, v46
	v_add_f32_e32 v51, v105, v52
	v_exp_f32_e32 v109, v45
	v_add_f32_e32 v50, v106, v51
	v_add_f32_e32 v49, v107, v50
	v_add_f32_e32 v46, v108, v49
	v_add_f32_e32 v45, v109, v46
	v_exp_f32_e32 v46, v44
	s_nop 0
	v_add_f32_e32 v44, v46, v45
	v_sub_f32_e32 v45, v47, v48
	v_exp_f32_e32 v47, v45
	s_nop 0
	v_add_f32_e32 v44, v47, v44
	v_mov_b32_e32 v45, v44
	v_mov_b32_e32 v48, v44
	s_nop 1
	v_permlane32_swap_b32_e32 v45, v48
	v_cndmask_b32_e64 v45, v45, v48, s[6:7]
	v_add_f32_e32 v44, v44, v45
	v_max_f32_e32 v44, 0xda24260, v44
	v_div_scale_f32 v45, s[2:3], v44, v44, 1.0
	v_rcp_f32_e32 v48, v45
	s_nop 0
	v_fma_f32 v49, -v45, v48, 1.0
	v_fmac_f32_e32 v48, v49, v48
	v_div_scale_f32 v49, vcc, 1.0, v44, 1.0
	v_mul_f32_e32 v50, v49, v48
	v_fma_f32 v51, -v45, v50, v49
	v_fmac_f32_e32 v50, v51, v48
	v_fma_f32 v45, -v45, v50, v49
	v_div_fmas_f32 v45, v45, v48, v50
	v_div_fixup_f32 v110, v45, v44, 1.0
	v_pk_mul_f32 v[0:1], v[0:1], v[110:111] op_sel_hi:[1,0]
	v_pk_mul_f32 v[2:3], v[2:3], v[110:111] op_sel_hi:[1,0]
	v_pk_mul_f32 v[64:65], v[16:17], v[110:111] op_sel_hi:[1,0]
	v_add_f32_e32 v16, v2, v3
	v_add_f32_e32 v17, v0, v1
	v_pk_mul_f32 v[66:67], v[18:19], v[110:111] op_sel_hi:[1,0]
	v_add_f32_e32 v16, v17, v16
	v_mov_b32_e32 v17, v3
	v_mov_b32_e32 v18, v3
	s_nop 1
	v_permlane32_swap_b32_e32 v17, v18
	v_cndmask_b32_e64 v17, v17, v18, s[6:7]
	v_pk_mul_f32 v[4:5], v[4:5], v[110:111] op_sel_hi:[1,0]
	v_pk_mul_f32 v[6:7], v[6:7], v[110:111] op_sel_hi:[1,0]
	v_cndmask_b32_e64 v18, v17, 0, s[8:9]
	v_add_f32_e32 v16, v18, v16
	v_add_f32_e32 v18, v6, v7
	v_add_f32_e32 v19, v4, v5
	v_pk_mul_f32 v[68:69], v[20:21], v[110:111] op_sel_hi:[1,0]
	v_add_f32_e32 v18, v19, v18
	v_mov_b32_e32 v19, v7
	v_mov_b32_e32 v20, v7
	s_nop 1
	v_permlane32_swap_b32_e32 v19, v20
	v_cndmask_b32_e64 v19, v19, v20, s[6:7]
	v_cndmask_b32_e64 v17, v19, v17, s[8:9]
	v_pk_mul_f32 v[8:9], v[8:9], v[110:111] op_sel_hi:[1,0]
	v_pk_mul_f32 v[10:11], v[10:11], v[110:111] op_sel_hi:[1,0]
	v_pk_mul_f32 v[48:49], v[32:33], v[110:111] op_sel_hi:[1,0]
	v_pk_mul_f32 v[32:33], v[96:97], v[110:111] op_sel_hi:[1,0]
	v_add_f32_e32 v17, v17, v18
	v_add_u32_e32 v96, 0xa800, v194
	ds_write2_b32 v96, v16, v17 offset1:2
	v_add_f32_e32 v16, v10, v11
	v_add_f32_e32 v17, v8, v9
	v_add_f32_e32 v16, v17, v16
	v_mov_b32_e32 v17, v11
	v_mov_b32_e32 v18, v11
	s_nop 1
	v_permlane32_swap_b32_e32 v17, v18
	v_cndmask_b32_e64 v17, v17, v18, s[6:7]
	v_pk_mul_f32 v[12:13], v[12:13], v[110:111] op_sel_hi:[1,0]
	v_pk_mul_f32 v[14:15], v[14:15], v[110:111] op_sel_hi:[1,0]
	v_cndmask_b32_e64 v18, v17, v19, s[8:9]
	v_add_f32_e32 v16, v18, v16
	v_add_f32_e32 v18, v14, v15
	v_add_f32_e32 v19, v12, v13
	v_add_f32_e32 v18, v19, v18
	v_mov_b32_e32 v19, v15
	v_mov_b32_e32 v20, v15
	s_nop 1
	v_permlane32_swap_b32_e32 v19, v20
	v_cndmask_b32_e64 v97, v19, v20, s[6:7]
	v_cndmask_b32_e64 v17, v97, v17, s[8:9]
	v_add_f32_e32 v17, v17, v18
	ds_write2_b32 v96, v16, v17 offset0:4 offset1:6
	v_pk_mul_f32 v[70:71], v[22:23], v[110:111] op_sel_hi:[1,0]
	v_cvt_pk_bf16_f32 v16, v0, v1
	v_cvt_pk_bf16_f32 v17, v2, v3
	ds_read_b64_tr_b16 v[0:1], v160 offset:18432
	ds_read_b64_tr_b16 v[2:3], v160 offset:19968
	ds_read_b64_tr_b16 v[20:21], v160 offset:21504
	ds_read_b64_tr_b16 v[22:23], v160 offset:23040
	v_cvt_pk_bf16_f32 v18, v4, v5
	v_cvt_pk_bf16_f32 v19, v6, v7
	v_pk_mul_f32 v[50:51], v[34:35], v[110:111] op_sel_hi:[1,0]
	v_pk_mul_f32 v[52:53], v[36:37], v[110:111] op_sel_hi:[1,0]
	v_pk_mul_f32 v[34:35], v[98:99], v[110:111] op_sel_hi:[1,0]
	v_pk_mul_f32 v[36:37], v[100:101], v[110:111] op_sel_hi:[1,0]
	v_cvt_pk_bf16_f32 v98, v8, v9
	v_cvt_pk_bf16_f32 v99, v10, v11
	v_cvt_pk_bf16_f32 v100, v12, v13
	v_cvt_pk_bf16_f32 v101, v14, v15
	s_waitcnt lgkmcnt(2)
	v_mfma_f32_32x32x16_bf16 v[0:15], v[0:3], v[16:19], 0
	v_mul_f32_e64 v54, v38, v110
	v_mul_f32_e64 v55, v39, v110
	v_mul_f32_e64 v56, v40, v110
	v_mul_f32_e64 v57, v41, v110
	v_mul_f32_e64 v38, v102, v110
	v_mul_f32_e64 v39, v103, v110
	v_pk_mul_f32 v[40:41], v[104:105], v[110:111] op_sel_hi:[1,0]
	v_pk_mul_f32 v[72:73], v[24:25], v[110:111] op_sel_hi:[1,0]
	v_pk_mul_f32 v[74:75], v[26:27], v[110:111] op_sel_hi:[1,0]
	v_pk_mul_f32 v[76:77], v[28:29], v[110:111] op_sel_hi:[1,0]
	s_waitcnt lgkmcnt(0)
	v_mfma_f32_32x32x16_bf16 v[0:15], v[20:23], v[98:101], v[0:15]
	ds_read_b64_tr_b16 v[20:21], v160 offset:18496
	ds_read_b64_tr_b16 v[22:23], v160 offset:20032
	ds_read_b64_tr_b16 v[102:103], v160 offset:21568
	ds_read_b64_tr_b16 v[104:105], v160 offset:23104
	v_mul_f32_e64 v78, v30, v110
	v_mul_f32_e64 v79, v31, v110
	v_pk_mul_f32 v[58:59], v[42:43], v[110:111] op_sel_hi:[1,0]
	v_pk_mul_f32 v[60:61], v[60:61], v[110:111] op_sel_hi:[1,0]
	v_pk_mul_f32 v[62:63], v[62:63], v[110:111] op_sel_hi:[1,0]
	v_pk_mul_f32 v[42:43], v[106:107], v[110:111] op_sel_hi:[1,0]
	v_pk_mul_f32 v[44:45], v[108:109], v[110:111] op_sel_hi:[1,0]
	s_waitcnt lgkmcnt(2)
	v_mfma_f32_32x32x16_bf16 v[16:31], v[20:23], v[16:19], 0
	v_mul_f32_e64 v46, v46, v110
	v_mul_f32_e64 v47, v47, v110
	s_waitcnt lgkmcnt(0)
	v_mfma_f32_32x32x16_bf16 v[16:31], v[102:105], v[98:101], v[16:31]
	v_add_f32_e32 v98, v66, v67
	v_add_f32_e32 v99, v64, v65
	v_add_f32_e32 v98, v99, v98
	v_mov_b32_e32 v99, v67
	v_mov_b32_e32 v100, v67
	s_nop 1
	v_permlane32_swap_b32_e32 v99, v100
	v_cndmask_b32_e64 v99, v99, v100, s[6:7]
	v_cndmask_b32_e64 v97, v99, v97, s[8:9]
	v_add_f32_e32 v97, v97, v98
	v_add_f32_e32 v98, v70, v71
	v_add_f32_e32 v100, v68, v69
	v_add_f32_e32 v98, v100, v98
	v_mov_b32_e32 v100, v71
	v_mov_b32_e32 v101, v71
	s_nop 1
	v_permlane32_swap_b32_e32 v100, v101
	v_cndmask_b32_e64 v100, v100, v101, s[6:7]
	v_cndmask_b32_e64 v99, v100, v99, s[8:9]
	v_add_f32_e32 v98, v99, v98
	ds_write2_b32 v96, v97, v98 offset0:8 offset1:10
	v_add_f32_e32 v97, v74, v75
	v_add_f32_e32 v98, v72, v73
	v_add_f32_e32 v97, v98, v97
	v_mov_b32_e32 v98, v75
	v_mov_b32_e32 v99, v75
	s_nop 1
	v_permlane32_swap_b32_e32 v98, v99
	v_cndmask_b32_e64 v98, v98, v99, s[6:7]
	v_cndmask_b32_e64 v99, v98, v100, s[8:9]
	v_add_f32_e32 v97, v99, v97
	v_add_f32_e32 v99, v78, v79
	v_add_f32_e32 v100, v76, v77
	v_add_f32_e32 v99, v100, v99
	v_mov_b32_e32 v100, v79
	v_mov_b32_e32 v101, v79
	s_nop 1
	v_permlane32_swap_b32_e32 v100, v101
	v_cndmask_b32_e64 v100, v100, v101, s[6:7]
	v_cndmask_b32_e64 v98, v100, v98, s[8:9]
	v_add_f32_e32 v98, v98, v99
	ds_write2_b32 v96, v97, v98 offset0:12 offset1:14
	v_cvt_pk_bf16_f32 v64, v64, v65
	v_cvt_pk_bf16_f32 v65, v66, v67
	v_cvt_pk_bf16_f32 v66, v68, v69
	v_cvt_pk_bf16_f32 v67, v70, v71
	v_cvt_pk_bf16_f32 v68, v72, v73
	v_cvt_pk_bf16_f32 v69, v74, v75
	v_cvt_pk_bf16_f32 v70, v76, v77
	v_cvt_pk_bf16_f32 v71, v78, v79
	ds_read_b64_tr_b16 v[72:73], v160 offset:24576
	ds_read_b64_tr_b16 v[74:75], v160 offset:26112
	ds_read_b64_tr_b16 v[76:77], v160 offset:27648
	ds_read_b64_tr_b16 v[78:79], v160 offset:29184
	s_waitcnt lgkmcnt(2)
	v_mfma_f32_32x32x16_bf16 v[0:15], v[72:75], v[64:67], v[0:15]
	s_waitcnt lgkmcnt(0)
	v_mfma_f32_32x32x16_bf16 v[0:15], v[76:79], v[68:71], v[0:15]
	ds_read_b64_tr_b16 v[72:73], v160 offset:24640
	ds_read_b64_tr_b16 v[74:75], v160 offset:26176
	ds_read_b64_tr_b16 v[76:77], v160 offset:27712
	ds_read_b64_tr_b16 v[78:79], v160 offset:29248
	s_waitcnt lgkmcnt(2)
	v_mfma_f32_32x32x16_bf16 v[16:31], v[72:75], v[64:67], v[16:31]
	v_add_f32_e32 v64, v50, v51
	v_add_f32_e32 v65, v48, v49
	v_add_f32_e32 v64, v65, v64
	v_mov_b32_e32 v65, v51
	v_mov_b32_e32 v66, v51
	s_nop 1
	v_permlane32_swap_b32_e32 v65, v66
	v_cndmask_b32_e64 v65, v65, v66, s[6:7]
	v_cndmask_b32_e64 v66, v65, v100, s[8:9]
	v_add_f32_e32 v64, v66, v64
	v_add_f32_e32 v66, v54, v55
	v_add_f32_e32 v67, v52, v53
	s_waitcnt lgkmcnt(0)
	v_mfma_f32_32x32x16_bf16 v[16:31], v[76:79], v[68:71], v[16:31]
	v_add_f32_e32 v66, v67, v66
	v_mov_b32_e32 v67, v55
	v_mov_b32_e32 v68, v55
	s_nop 1
	v_permlane32_swap_b32_e32 v67, v68
	v_cndmask_b32_e64 v67, v67, v68, s[6:7]
	v_cndmask_b32_e64 v65, v67, v65, s[8:9]
	v_add_f32_e32 v65, v65, v66
	ds_write2_b32 v96, v64, v65 offset0:16 offset1:18
	v_add_f32_e32 v64, v58, v59
	v_add_f32_e32 v65, v56, v57
	v_add_f32_e32 v64, v65, v64
	v_mov_b32_e32 v65, v59
	v_mov_b32_e32 v66, v59
	s_nop 1
	v_permlane32_swap_b32_e32 v65, v66
	v_cndmask_b32_e64 v65, v65, v66, s[6:7]
	v_cndmask_b32_e64 v66, v65, v67, s[8:9]
	v_add_f32_e32 v64, v66, v64
	v_add_f32_e32 v66, v62, v63
	v_add_f32_e32 v67, v60, v61
	v_add_f32_e32 v66, v67, v66
	v_mov_b32_e32 v67, v63
	v_mov_b32_e32 v68, v63
	s_nop 1
	v_permlane32_swap_b32_e32 v67, v68
	v_cndmask_b32_e64 v67, v67, v68, s[6:7]
	v_cndmask_b32_e64 v65, v67, v65, s[8:9]
	v_add_f32_e32 v65, v65, v66
	ds_write2_b32 v96, v64, v65 offset0:20 offset1:22
	v_cvt_pk_bf16_f32 v48, v48, v49
	v_cvt_pk_bf16_f32 v49, v50, v51
	v_cvt_pk_bf16_f32 v50, v52, v53
	v_cvt_pk_bf16_f32 v51, v54, v55
	v_cvt_pk_bf16_f32 v52, v56, v57
	v_cvt_pk_bf16_f32 v53, v58, v59
	v_cvt_pk_bf16_f32 v54, v60, v61
	v_cvt_pk_bf16_f32 v55, v62, v63
	ds_read_b64_tr_b16 v[56:57], v160 offset:30720
	ds_read_b64_tr_b16 v[58:59], v160 offset:32256
	ds_read_b64_tr_b16 v[60:61], v160 offset:33792
	ds_read_b64_tr_b16 v[62:63], v160 offset:35328
	s_waitcnt lgkmcnt(2)
	v_mfma_f32_32x32x16_bf16 v[0:15], v[56:59], v[48:51], v[0:15]
	s_waitcnt lgkmcnt(0)
	v_mfma_f32_32x32x16_bf16 v[0:15], v[60:63], v[52:55], v[0:15]
	ds_read_b64_tr_b16 v[56:57], v160 offset:30784
	ds_read_b64_tr_b16 v[58:59], v160 offset:32320
	ds_read_b64_tr_b16 v[60:61], v160 offset:33856
	ds_read_b64_tr_b16 v[62:63], v160 offset:35392
	s_waitcnt lgkmcnt(2)
	v_mfma_f32_32x32x16_bf16 v[16:31], v[56:59], v[48:51], v[16:31]
	v_add_f32_e32 v48, v34, v35
	v_add_f32_e32 v49, v32, v33
	v_add_f32_e32 v48, v49, v48
	v_mov_b32_e32 v49, v35
	v_mov_b32_e32 v50, v35
	s_nop 1
	v_permlane32_swap_b32_e32 v49, v50
	v_cndmask_b32_e64 v49, v49, v50, s[6:7]
	v_cndmask_b32_e64 v50, v49, v67, s[8:9]
	v_add_f32_e32 v48, v50, v48
	v_add_f32_e32 v50, v38, v39
	v_add_f32_e32 v51, v36, v37
	s_waitcnt lgkmcnt(0)
	v_mfma_f32_32x32x16_bf16 v[16:31], v[60:63], v[52:55], v[16:31]
	v_add_f32_e32 v50, v51, v50
	v_mov_b32_e32 v51, v39
	v_mov_b32_e32 v52, v39
	s_nop 1
	v_permlane32_swap_b32_e32 v51, v52
	v_cndmask_b32_e64 v51, v51, v52, s[6:7]
	v_cndmask_b32_e64 v49, v51, v49, s[8:9]
	v_add_f32_e32 v49, v49, v50
	ds_write2_b32 v96, v48, v49 offset0:24 offset1:26
	v_add_f32_e32 v48, v42, v43
	v_add_f32_e32 v49, v40, v41
	v_add_f32_e32 v48, v49, v48
	v_mov_b32_e32 v49, v43
	v_mov_b32_e32 v50, v43
	s_nop 1
	v_permlane32_swap_b32_e32 v49, v50
	v_cndmask_b32_e64 v49, v49, v50, s[6:7]
	v_cndmask_b32_e64 v50, v49, v51, s[8:9]
	v_add_f32_e32 v48, v50, v48
	v_add_f32_e32 v50, v46, v47
	v_add_f32_e32 v51, v44, v45
	v_add_f32_e32 v50, v51, v50
	v_mov_b32_e32 v51, v47
	v_mov_b32_e32 v52, v47
	s_nop 1
	v_permlane32_swap_b32_e32 v51, v52
	v_cndmask_b32_e64 v51, v51, v52, s[6:7]
	v_cndmask_b32_e64 v49, v51, v49, s[8:9]
	v_add_f32_e32 v49, v49, v50
	ds_write2_b32 v96, v48, v49 offset0:28 offset1:30
	v_cvt_pk_bf16_f32 v32, v32, v33
	v_cvt_pk_bf16_f32 v33, v34, v35
	v_cvt_pk_bf16_f32 v34, v36, v37
	v_cvt_pk_bf16_f32 v35, v38, v39
	v_cvt_pk_bf16_f32 v36, v40, v41
	v_cvt_pk_bf16_f32 v37, v42, v43
	v_cvt_pk_bf16_f32 v38, v44, v45
	v_cvt_pk_bf16_f32 v39, v46, v47
	ds_read_b64_tr_b16 v[40:41], v160 offset:36864
	ds_read_b64_tr_b16 v[42:43], v160 offset:38400
	ds_read_b64_tr_b16 v[44:45], v160 offset:39936
	ds_read_b64_tr_b16 v[46:47], v160 offset:41472
	s_waitcnt lgkmcnt(2)
	v_mfma_f32_32x32x16_bf16 v[0:15], v[40:43], v[32:35], v[0:15]
	s_waitcnt lgkmcnt(0)
	v_mfma_f32_32x32x16_bf16 v[0:15], v[44:47], v[36:39], v[0:15]
	ds_read_b64_tr_b16 v[40:41], v160 offset:36928
	ds_read_b64_tr_b16 v[42:43], v160 offset:38464
	ds_read_b64_tr_b16 v[44:45], v160 offset:40000
	ds_read_b64_tr_b16 v[46:47], v160 offset:41536
	s_waitcnt lgkmcnt(2)
	v_mfma_f32_32x32x16_bf16 v[16:31], v[40:43], v[32:35], v[16:31]
	s_nop 5
	v_mul_f32_e32 v0, v128, v0
	v_mul_f32_e32 v1, v128, v1
	ds_write2st64_b32 v195, v0, v1 offset1:8
	v_mul_f32_e32 v0, v128, v2
	v_mul_f32_e32 v1, v128, v3
	ds_write2st64_b32 v195, v0, v1 offset0:16 offset1:24
	v_mul_f32_e32 v0, v128, v4
	s_waitcnt lgkmcnt(2)
	v_mfma_f32_32x32x16_bf16 v[16:31], v[44:47], v[36:39], v[16:31]
	v_mul_f32_e32 v1, v128, v5
	ds_write2st64_b32 v195, v0, v1 offset0:32 offset1:40
	v_mul_f32_e32 v0, v128, v6
	v_mul_f32_e32 v1, v128, v7
	ds_write2st64_b32 v195, v0, v1 offset0:48 offset1:56
	v_mul_f32_e32 v0, v128, v8
	v_mul_f32_e32 v1, v128, v9
	ds_write2st64_b32 v195, v0, v1 offset0:64 offset1:72
	v_mul_f32_e32 v0, v128, v10
	v_mul_f32_e32 v1, v128, v11
	ds_write2st64_b32 v195, v0, v1 offset0:80 offset1:88
	v_mul_f32_e32 v0, v128, v12
	v_mul_f32_e32 v1, v128, v13
	ds_write2st64_b32 v195, v0, v1 offset0:96 offset1:104
	v_mul_f32_e32 v0, v128, v14
	v_mul_f32_e32 v1, v128, v15
	ds_write2st64_b32 v195, v0, v1 offset0:112 offset1:120
	v_mul_f32_e32 v0, v128, v16
	v_mul_f32_e32 v1, v128, v17
	ds_write2st64_b32 v195, v0, v1 offset0:128 offset1:136
	v_mul_f32_e32 v0, v128, v18
	v_mul_f32_e32 v1, v128, v19
	ds_write2st64_b32 v195, v0, v1 offset0:144 offset1:152
	v_mul_f32_e32 v0, v128, v20
	v_mul_f32_e32 v1, v128, v21
	ds_write2st64_b32 v195, v0, v1 offset0:160 offset1:168
	v_mul_f32_e32 v0, v128, v22
	v_mul_f32_e32 v1, v128, v23
	ds_write2st64_b32 v195, v0, v1 offset0:176 offset1:184
	v_mul_f32_e32 v0, v128, v24
	v_mul_f32_e32 v1, v128, v25
	ds_write2st64_b32 v195, v0, v1 offset0:192 offset1:200
	v_mul_f32_e32 v0, v128, v26
	v_mul_f32_e32 v1, v128, v27
	ds_write2st64_b32 v195, v0, v1 offset0:208 offset1:216
	v_mul_f32_e32 v0, v128, v28
	v_mul_f32_e32 v1, v128, v29
	ds_write2st64_b32 v195, v0, v1 offset0:224 offset1:232
	v_mul_f32_e32 v0, v128, v30
	v_mul_f32_e32 v1, v128, v31
	ds_write2st64_b32 v195, v0, v1 offset0:240 offset1:248
	s_waitcnt lgkmcnt(0)
	s_barrier
	s_cbranch_scc0 .LBB0_1004
	s_add_i32 s2, s93, -2
	v_mov_b32_e32 v4, -1.0
	s_mov_b64 s[4:5], exec
	v_readlane_b32 s12, v240, 45
	v_readlane_b32 s13, v240, 46
	s_and_b64 s[12:13], s[4:5], s[12:13]
	s_mov_b64 exec, s[12:13]
	s_cbranch_execz .LBB0_943
	ds_read2st64_b32 v[0:1], v197 offset0:168 offset1:201
	ds_read_b32 v2, v197 offset:59904
	ds_read_b32 v3, v198 offset:25344
	v_cmp_ge_u32_e32 vcc, s2, v196
	s_waitcnt lgkmcnt(2)
	v_add_f32_e32 v0, v0, v1
	s_waitcnt lgkmcnt(1)
	v_add_f32_e32 v0, v0, v2
	s_waitcnt lgkmcnt(0)
	v_add_f32_e32 v0, v0, v3
	v_cndmask_b32_e32 v4, -1.0, v0, vcc
